# scan: store-path copy of the loop tail with wait counts that leave the four state-image stores in flight
# speedup vs baseline: 1.0378x; 1.0032x over previous
; #define LAS __attribute__((address_space(3)))
; template <int BR> DI void scan_item(PARAMS P, int l, int g, int seq, int h, int vs, int ct, int lane, LAS unsigned char* wlds) {
;     ...
;         asm volatile("s_waitcnt lgkmcnt(0)" ::: "memory");
; #pragma unroll
;         for (int k = 0; k < 4; ++k) { const int id_ = lane + 64 * k, rw_ = id_ >> 2, q_ = id_ & 3; *(LAS u32x4*)(Atl + rw_ * 40 + 8 * q_) = ta[k]; *(LAS u32x4*)(Btl + rw_ * 40 + 8 * q_) = tb[k]; }
;         asm volatile("s_waitcnt lgkmcnt(0)" ::: "memory");
;         bf16x8 ac[4], bc[4];
;         {
;             typedef short s16x4_t __attribute__((ext_vector_type(4)));
;             const unsigned lo_ = (unsigned)((8 * hh + ((lane & 15) >> 2)) * 80 + (16 * ((lane >> 4) & 1) + 4 * (lane & 3)) * 2);
;             const unsigned aad = (unsigned)(size_t)Atl + lo_, bad = (unsigned)(size_t)Btl + lo_;
;             s16x4_t al_[4], ah_[4], bl_[4], bh_[4];
; #pragma unroll
;             for (int ks = 0; ks < 4; ++ks) {
;                 asm volatile("ds_read_b64_tr_b16 %0, %1 offset:%c2" : "=&v"(al_[ks]) : "v"(aad), "i"(ks * 1280) : "memory");
;                 asm volatile("ds_read_b64_tr_b16 %0, %1 offset:%c2" : "=&v"(ah_[ks]) : "v"(aad), "i"(ks * 1280 + 320) : "memory");
;                 asm volatile("ds_read_b64_tr_b16 %0, %1 offset:%c2" : "=&v"(bl_[ks]) : "v"(bad), "i"(ks * 1280) : "memory");
;                 asm volatile("ds_read_b64_tr_b16 %0, %1 offset:%c2" : "=&v"(bh_[ks]) : "v"(bad), "i"(ks * 1280 + 320) : "memory");
;             }
;             asm volatile("s_waitcnt lgkmcnt(0)" ::: "memory");
; #pragma unroll
;             for (int ks = 0; ks < 4; ++ks) { ac[ks] = __builtin_shufflevector(al_[ks], ah_[ks], 0, 1, 2, 3, 4, 5, 6, 7); bc[ks] = __builtin_shufflevector(bl_[ks], bh_[ks], 0, 1, 2, 3, 4, 5, 6, 7); }
;         }
;         if (ci >= 0) {
;             bf16_t* sp = SP + (size_t)(cid * 4 + h) * 128 * DK + (size_t)((ct * 4) * 2 + hh) * 512 + (size_t)(32 * vs + r) * 4;
; #pragma unroll
;             for (int q4 = 0; q4 < 4; ++q4) { u32x2 w; w.x = cvt_pk_bf16(S[4 * q4], S[4 * q4 + 1]); w.y = cvt_pk_bf16(S[4 * q4 + 2], S[4 * q4 + 3]); *(u32x2*)(sp + q4 * 1024) = w; }
;             if (own_n) { NPv[(size_t)(cid * 4 + h) * 128 + lane] = n0; NPv[(size_t)(cid * 4 + h) * 128 + 64 + lane] = n1; if (lane == 0) MPv[cid * 4 + h] = m; }
;         }
;         float so = 1.f, sn = 1.f;
.LBB0_571:
	s_waitcnt lgkmcnt(0)
	ds_write_b128 v150, v[82:85]
	ds_write_b128 v150, v[12:15] offset:5120
	ds_write_b128 v150, v[86:89] offset:1280
	ds_write_b128 v150, v[8:11] offset:6400
	ds_write_b128 v150, v[90:93] offset:2560
	ds_write_b128 v150, v[4:7] offset:7680
	ds_write_b128 v150, v[94:97] offset:3840
	ds_write_b128 v150, v[0:3] offset:8960
	s_waitcnt lgkmcnt(0)
	ds_read_b64_tr_b16 v[0:1], v147 offset:0
	ds_read_b64_tr_b16 v[2:3], v147 offset:320
	ds_read_b64_tr_b16 v[4:5], v148 offset:0
	ds_read_b64_tr_b16 v[6:7], v148 offset:320
	ds_read_b64_tr_b16 v[82:83], v147 offset:1280
	ds_read_b64_tr_b16 v[84:85], v147 offset:1600
	ds_read_b64_tr_b16 v[86:87], v148 offset:1280
	ds_read_b64_tr_b16 v[88:89], v148 offset:1600
	ds_read_b64_tr_b16 v[90:91], v147 offset:2560
	ds_read_b64_tr_b16 v[92:93], v147 offset:2880
	ds_read_b64_tr_b16 v[94:95], v148 offset:2560
	ds_read_b64_tr_b16 v[96:97], v148 offset:2880
	ds_read_b64_tr_b16 v[98:99], v147 offset:3840
	ds_read_b64_tr_b16 v[100:101], v147 offset:4160
	ds_read_b64_tr_b16 v[102:103], v148 offset:3840
	ds_read_b64_tr_b16 v[104:105], v148 offset:4160
	s_waitcnt lgkmcnt(0)
	s_cmp_lt_i32 s51, 0
	s_cbranch_scc1 .LBB0_568
	s_lshl_b32 s35, s63, 2
	s_or_b32 s66, s35, s87
	s_ashr_i32 s67, s66, 31
	s_lshl_b64 s[66:67], s[66:67], 14
	v_lshl_add_u64 v[8:9], v[140:141], 0, s[66:67]
	v_cvt_pk_bf16_f32 v10, v116, v117
	v_cvt_pk_bf16_f32 v11, v120, v121
	global_store_dwordx2 v[8:9], v[10:11], off
	v_cvt_pk_bf16_f32 v10, v122, v123
	v_cvt_pk_bf16_f32 v11, v124, v125
	global_store_dwordx2 v[8:9], v[10:11], off offset:2048
	v_add_co_u32_e32 v8, vcc, 0x1000, v8
	v_cvt_pk_bf16_f32 v10, v126, v127
	v_cvt_pk_bf16_f32 v11, v128, v129
	v_addc_co_u32_e32 v9, vcc, 0, v9, vcc
	global_store_dwordx2 v[8:9], v[10:11], off
	v_cvt_pk_bf16_f32 v10, v130, v131
	v_cvt_pk_bf16_f32 v11, v132, v133
	global_store_dwordx2 v[8:9], v[10:11], off offset:2048
	v_mfma_f32_32x32x16_bf16 v[0:15], v[0:3], v[4:7], 0
	v_add_u32_e32 v138, 64, v138
	v_add_u32_e32 v142, 0x100, v142
	s_and_b64 vcc, exec, s[6:7]
	s_mov_b32 s63, s21
	s_mov_b32 s51, s50
	v_mfma_f32_32x32x16_bf16 v[0:15], v[82:85], v[86:89], v[0:15]
	s_waitcnt vmcnt(15)
	v_mov_b64_e32 v[84:85], v[22:23]
	s_waitcnt vmcnt(13)
	v_mov_b64_e32 v[88:89], v[30:31]
	v_mov_b64_e32 v[82:83], v[20:21]
	v_mov_b64_e32 v[86:87], v[28:29]
	v_mfma_f32_32x32x16_bf16 v[0:15], v[90:93], v[94:97], v[0:15]
	s_waitcnt vmcnt(11)
	v_mov_b64_e32 v[92:93], v[40:41]
	s_waitcnt vmcnt(9)
	v_mov_b64_e32 v[96:97], v[48:49]
	v_mov_b64_e32 v[90:91], v[38:39]
	v_mov_b64_e32 v[94:95], v[46:47]
	v_mfma_f32_32x32x16_bf16 v[0:15], v[98:101], v[102:105], v[0:15]
	s_nop 11
	v_pk_fma_f32 v[116:117], v[50:51], v[116:117], v[0:1]
	v_pk_fma_f32 v[132:133], v[132:133], v[64:65], v[14:15]
	v_pk_fma_f32 v[130:131], v[130:131], v[62:63], v[12:13]
	v_pk_fma_f32 v[128:129], v[128:129], v[60:61], v[10:11]
	v_pk_fma_f32 v[126:127], v[126:127], v[58:59], v[8:9]
	v_pk_fma_f32 v[124:125], v[124:125], v[56:57], v[6:7]
	v_pk_fma_f32 v[122:123], v[122:123], v[54:55], v[4:5]
	v_pk_fma_f32 v[120:121], v[120:121], v[52:53], v[2:3]
	v_mov_b64_e32 v[12:13], v[16:17]
	v_mov_b64_e32 v[8:9], v[24:25]
	v_mov_b64_e32 v[4:5], v[34:35]
	s_waitcnt vmcnt(8)
	v_mov_b64_e32 v[0:1], v[42:43]
	v_mov_b64_e32 v[14:15], v[18:19]
	v_mov_b64_e32 v[10:11], v[26:27]
	v_mov_b64_e32 v[6:7], v[36:37]
	v_mov_b64_e32 v[2:3], v[44:45]
	s_waitcnt vmcnt(7)
	v_mov_b32_e32 v50, v66
	v_mov_b32_e32 v51, v67
	v_mov_b32_e32 v52, v68
	v_mov_b32_e32 v53, v69
	s_waitcnt vmcnt(6)
	v_mov_b32_e32 v54, v70
	v_mov_b32_e32 v55, v71
	v_mov_b32_e32 v56, v72
	v_mov_b32_e32 v57, v73
	s_waitcnt vmcnt(5)
	v_mov_b32_e32 v58, v74
	v_mov_b32_e32 v59, v75
	v_mov_b32_e32 v60, v76
	v_mov_b32_e32 v61, v77
	s_waitcnt vmcnt(4)
	v_mov_b32_e32 v62, v78
	v_mov_b32_e32 v63, v79
	v_mov_b32_e32 v64, v80
	v_mov_b32_e32 v65, v81
	s_cbranch_vccnz .LBB0_573
	s_branch .LBB0_569

; #define MFMA32(a, b, c) __builtin_amdgcn_mfma_f32_32x32x16_bf16((a), (b), (c), 0, 0, 0)
; template <int BR> DI void scan_item(PARAMS P, int l, int g, int seq, int h, int vs, int ct, int lane, LAS unsigned char* wlds) {
;     ...
;         float so = 1.f, sn = 1.f;
;         if (BR == 0) so = exp2f((float)((cid == 136) ? 16 : 64) * lg);
;         if (BR == 1) { const float bl = blc, ml = mlc; const float mn = fmaxf(bl + m, ml); so = __expf(bl + m - mn); sn = __expf(ml - mn); m = mn;
;             n0 = so * n0 + sn * dn0c; n1 = so * n1 + sn * dn1c; }
;         {
;             f32x16 ds;
; #pragma unroll
;             for (int i = 0; i < 16; ++i) ds[i] = 0.f;
; #pragma unroll
;             for (int ks = 0; ks < 4; ++ks) ds = MFMA32(ac[ks], bc[ks], ds);
;             if (BR == 2) {
; #pragma unroll
;                 for (int i = 0; i < 16; ++i) S[i] = decc[i] * S[i] + ds[i];
;             } else {
; #pragma unroll
;                 for (int i = 0; i < 16; ++i) S[i] = so * S[i] + sn * ds[i];
;             }
;         }
.Lscan_m_st:
	v_mfma_f32_32x32x16_bf16 v[0:15], v[0:3], v[4:7], 0
	v_add_u32_e32 v102, 64, v102
	s_add_i32 s20, s20, 4
	s_add_i32 s70, s70, 8
	s_and_b64 vcc, exec, s[74:75]
	v_mfma_f32_32x32x16_bf16 v[0:15], v[66:69], v[70:73], v[0:15]
	v_add_f32_e32 v66, v118, v104
	v_max_f32_e32 v67, v105, v105
	v_max_f32_e32 v118, v66, v67
	v_sub_f32_e32 v67, v66, v118
	v_sub_f32_e32 v66, v105, v118
	v_mul_f32_e32 v66, 0x3fb8aa3b, v66
	v_exp_f32_e32 v66, v66
	v_mfma_f32_32x32x16_bf16 v[0:15], v[58:61], v[62:65], v[0:15]
	v_mul_f32_e32 v58, 0x3fb8aa3b, v67
	v_exp_f32_e32 v58, v58
	v_pk_mul_f32 v[60:61], v[98:99], v[66:67] op_sel_hi:[1,0]
	s_nop 0
	v_pk_fma_f32 v[92:93], v[92:93], v[58:59], v[60:61] op_sel_hi:[1,0,1]
	v_mfma_f32_32x32x16_bf16 v[0:15], v[50:53], v[54:57], v[0:15]
	s_nop 11
	v_pk_mul_f32 v[0:1], v[66:67], v[0:1] op_sel_hi:[0,1]
	v_pk_mul_f32 v[2:3], v[66:67], v[2:3] op_sel_hi:[0,1]
	v_pk_mul_f32 v[4:5], v[66:67], v[4:5] op_sel_hi:[0,1]
	v_pk_mul_f32 v[6:7], v[66:67], v[6:7] op_sel_hi:[0,1]
	v_pk_mul_f32 v[8:9], v[66:67], v[8:9] op_sel_hi:[0,1]
	v_pk_mul_f32 v[10:11], v[66:67], v[10:11] op_sel_hi:[0,1]
	v_pk_mul_f32 v[12:13], v[66:67], v[12:13] op_sel_hi:[0,1]
	v_pk_mul_f32 v[14:15], v[66:67], v[14:15] op_sel_hi:[0,1]
	v_pk_fma_f32 v[74:75], v[58:59], v[74:75], v[0:1] op_sel_hi:[0,1,1]
	v_pk_fma_f32 v[78:79], v[78:79], v[58:59], v[2:3] op_sel_hi:[1,0,1]
	v_pk_fma_f32 v[80:81], v[80:81], v[58:59], v[4:5] op_sel_hi:[1,0,1]
	v_pk_fma_f32 v[82:83], v[82:83], v[58:59], v[6:7] op_sel_hi:[1,0,1]
	v_pk_fma_f32 v[84:85], v[84:85], v[58:59], v[8:9] op_sel_hi:[1,0,1]
	v_pk_fma_f32 v[86:87], v[86:87], v[58:59], v[10:11] op_sel_hi:[1,0,1]
	v_pk_fma_f32 v[88:89], v[88:89], v[58:59], v[12:13] op_sel_hi:[1,0,1]
	v_pk_fma_f32 v[90:91], v[90:91], v[58:59], v[14:15] op_sel_hi:[1,0,1]
	s_cbranch_vccnz .LBB0_633
	s_waitcnt vmcnt(11)
	v_mov_b64_e32 v[0:1], v[16:17]
	s_waitcnt vmcnt(9)
	v_mov_b64_e32 v[8:9], v[24:25]
	s_waitcnt vmcnt(7)
	v_mov_b64_e32 v[52:53], v[36:37]
	s_waitcnt vmcnt(5)
	v_mov_b64_e32 v[60:61], v[44:45]
	v_mov_b64_e32 v[4:5], v[20:21]
	v_mov_b64_e32 v[12:13], v[28:29]
	v_mov_b64_e32 v[56:57], v[40:41]
	v_mov_b64_e32 v[64:65], v[48:49]
	v_mov_b64_e32 v[2:3], v[18:19]
	v_mov_b64_e32 v[10:11], v[26:27]
	v_mov_b64_e32 v[50:51], v[34:35]
	v_mov_b64_e32 v[58:59], v[42:43]
	v_mov_b64_e32 v[6:7], v[22:23]
	v_mov_b64_e32 v[14:15], v[30:31]
	v_mov_b64_e32 v[54:55], v[38:39]
	v_mov_b64_e32 v[62:63], v[46:47]
	s_mov_b32 s91, s21
	s_mov_b32 s78, s53
	s_waitcnt vmcnt(4)
	v_mov_b64_e32 v[104:105], v[116:117]
	v_mov_b32_e32 v98, v77
	v_mov_b32_e32 v99, v103
	s_branch .LBB0_620

; __device__ __forceinline__ unsigned cvt_pk_bf16(float lo, float hi) { const f32x2_cv v = {lo, hi}; const bf16x2_cv b = __builtin_convertvector(v, bf16x2_cv); return __builtin_bit_cast(unsigned, b); }
; #define MFMA32(a, b, c) __builtin_amdgcn_mfma_f32_32x32x16_bf16((a), (b), (c), 0, 0, 0)
; template <int BR> DI void scan_item(PARAMS P, int l, int g, int seq, int h, int vs, int ct, int lane, LAS unsigned char* wlds) {
;     ...
;         if (ci >= 0) {
;             bf16_t* sp = SP + (size_t)(cid * 4 + h) * 128 * DK + (size_t)((ct * 4) * 2 + hh) * 512 + (size_t)(32 * vs + r) * 4;
; #pragma unroll
;             for (int q4 = 0; q4 < 4; ++q4) { u32x2 w; w.x = cvt_pk_bf16(S[4 * q4], S[4 * q4 + 1]); w.y = cvt_pk_bf16(S[4 * q4 + 2], S[4 * q4 + 3]); *(u32x2*)(sp + q4 * 1024) = w; }
;             if (own_n) { NPv[(size_t)(cid * 4 + h) * 128 + lane] = n0; NPv[(size_t)(cid * 4 + h) * 128 + 64 + lane] = n1; if (lane == 0) MPv[cid * 4 + h] = m; }
;         }
;         float so = 1.f, sn = 1.f;
;         if (BR == 0) so = exp2f((float)((cid == 136) ? 16 : 64) * lg);
;         if (BR == 1) { const float bl = blc, ml = mlc; const float mn = fmaxf(bl + m, ml); so = __expf(bl + m - mn); sn = __expf(ml - mn); m = mn;
;             n0 = so * n0 + sn * dn0c; n1 = so * n1 + sn * dn1c; }
;         {
;             f32x16 ds;
; #pragma unroll
;             for (int i = 0; i < 16; ++i) ds[i] = 0.f;
; #pragma unroll
;             for (int ks = 0; ks < 4; ++ks) ds = MFMA32(ac[ks], bc[ks], ds);
;             if (BR == 2) {
; #pragma unroll
;                 for (int i = 0; i < 16; ++i) S[i] = decc[i] * S[i] + ds[i];
;             } else {
; #pragma unroll
;                 for (int i = 0; i < 16; ++i) S[i] = so * S[i] + sn * ds[i];
;             }
;         }
.LBB0_680:
	s_andn2_b64 vcc, exec, s[20:21]
	s_cbranch_vccnz .LBB0_675
	s_lshl_b32 s20, s62, 2
	s_or_b32 s20, s20, s87
	s_ashr_i32 s21, s20, 31
	s_lshl_b64 s[20:21], s[20:21], 14
	v_lshl_add_u64 v[8:9], v[98:99], 0, s[20:21]
	v_cvt_pk_bf16_f32 v10, v74, v75
	v_cvt_pk_bf16_f32 v11, v78, v79
	global_store_dwordx2 v[8:9], v[10:11], off
	v_cvt_pk_bf16_f32 v10, v80, v81
	v_cvt_pk_bf16_f32 v11, v82, v83
	global_store_dwordx2 v[8:9], v[10:11], off offset:2048
	v_add_co_u32_e32 v8, vcc, 0x1000, v8
	v_cvt_pk_bf16_f32 v10, v84, v85
	v_cvt_pk_bf16_f32 v11, v86, v87
	v_addc_co_u32_e32 v9, vcc, 0, v9, vcc
	global_store_dwordx2 v[8:9], v[10:11], off
	v_cvt_pk_bf16_f32 v10, v88, v89
	v_cvt_pk_bf16_f32 v11, v90, v91
	global_store_dwordx2 v[8:9], v[10:11], off offset:2048
	v_mfma_f32_32x32x16_bf16 v[0:15], v[0:3], v[4:7], 0
	s_cmpk_eq_i32 s62, 0x88
	s_cselect_b32 s20, 16, 64
	v_cvt_f32_ubyte0_e32 v97, s20
	v_mul_f32_e32 v100, v77, v97
	v_cmp_gt_f32_e32 vcc, s22, v100
	s_and_b64 s[20:21], vcc, exec
	s_cselect_b32 s20, 0xffffffc0, 0
	v_mfma_f32_32x32x16_bf16 v[0:15], v[50:53], v[54:57], v[0:15]
	v_cndmask_b32_e32 v50, 0, v232, vcc
	v_fmac_f32_e32 v50, v77, v97
	v_exp_f32_e32 v50, v50
	s_waitcnt vmcnt(9)
	v_mov_b64_e32 v[56:57], v[30:31]
	v_add_u32_e32 v96, 64, v96
	s_and_b64 vcc, exec, s[6:7]
	v_ldexp_f32 v50, v50, s20
	v_mfma_f32_32x32x16_bf16 v[0:15], v[58:61], v[62:65], v[0:15]
	s_waitcnt vmcnt(7)
	v_mov_b64_e32 v[60:61], v[40:41]
	s_waitcnt vmcnt(5)
	v_mov_b64_e32 v[64:65], v[48:49]
	v_mov_b64_e32 v[54:55], v[28:29]
	v_mov_b64_e32 v[58:59], v[38:39]
	v_mov_b64_e32 v[62:63], v[46:47]
	s_mov_b32 s62, s51
	s_mov_b32 s20, s60
	v_mfma_f32_32x32x16_bf16 v[0:15], v[66:69], v[70:73], v[0:15]
	s_nop 11
	v_pk_fma_f32 v[74:75], v[50:51], v[74:75], v[0:1] op_sel_hi:[0,1,1]
	v_pk_fma_f32 v[78:79], v[78:79], v[50:51], v[2:3] op_sel_hi:[1,0,1]
	v_pk_fma_f32 v[80:81], v[80:81], v[50:51], v[4:5] op_sel_hi:[1,0,1]
	v_pk_fma_f32 v[82:83], v[82:83], v[50:51], v[6:7] op_sel_hi:[1,0,1]
	v_pk_fma_f32 v[84:85], v[84:85], v[50:51], v[8:9] op_sel_hi:[1,0,1]
	v_pk_fma_f32 v[86:87], v[86:87], v[50:51], v[10:11] op_sel_hi:[1,0,1]
	v_pk_fma_f32 v[88:89], v[88:89], v[50:51], v[12:13] op_sel_hi:[1,0,1]
	v_pk_fma_f32 v[90:91], v[90:91], v[50:51], v[14:15] op_sel_hi:[1,0,1]
	v_mov_b64_e32 v[12:13], v[16:17]
	v_mov_b64_e32 v[8:9], v[24:25]
	v_mov_b64_e32 v[4:5], v[34:35]
	s_waitcnt vmcnt(4)
	v_mov_b64_e32 v[0:1], v[42:43]
	v_mov_b64_e32 v[52:53], v[22:23]
	v_mov_b64_e32 v[14:15], v[18:19]
	v_mov_b64_e32 v[10:11], v[26:27]
	v_mov_b64_e32 v[6:7], v[36:37]
	v_mov_b64_e32 v[2:3], v[44:45]
	v_mov_b64_e32 v[50:51], v[20:21]
	s_cbranch_vccnz .LBB0_682
	s_branch .LBB0_676
